# inproj tile order: partial last M-group (1 M-tile) spread over 29 blocks instead of 16, removing a 1-tile tail
# speedup vs baseline: 1.0029x; 1.0029x over previous
;   DI bool next(int& mt, int& nt) {
;     for (;;) {
;       const int s = j + nb * k; ++k;
;       const int g = s / (2 * NN), r = s - g * (2 * NN);
;       if (g * 2 >= cnt) return false;
;       const int i = g * 2 + (r & 1);
;       if (i >= cnt) continue;
;       mt = x + 8 * i; nt = r >> 1; return true;
; __device__ void phase_inproj(const Params& p, int l, char* lds) {
;     ...
;   GemmOrder ord; ord.init(NTOK / 128, 29);
;   int mt, nt;
;   while (ord.next(mt, nt)) {
.LBB0_910:
	v_readlane_b32 s4, v236, 9
	s_mul_i32 s6, s60, s4
	v_readlane_b32 s4, v236, 20
	s_add_i32 s6, s6, s4
	s_mul_hi_u32 s4, s6, 0x8d3dcb09
	s_lshr_b32 s7, s4, 6
	s_lshl_b32 s4, s7, 2
	v_readlane_b32 s49, v236, 10
	s_cmp_ge_u32 s4, s49
	v_readlane_b32 s5, v236, 21
	s_cbranch_scc1 .LBB0_914
	s_mul_i32 s2, s7, 0xffffff8c
	s_add_i32 s2, s2, s6
	s_add_i32 s5, s4, 1
	s_cmp_eq_u32 s5, s49
	s_cbranch_scc1 .Lord_partial
	s_and_b32 s5, s6, 3
	s_or_b32 s48, s4, s5
	s_cmp_ge_u32 s48, s49
	s_mov_b64 s[4:5], 0
	s_cbranch_scc1 .LBB0_913
	s_ashr_i32 s63, s2, 2
.Lord_common:
	s_lshl_b32 s2, s48, 3
	v_readlane_b32 s3, v236, 44
	s_or_b32 s50, s2, s3
	s_mov_b64 s[2:3], -1
	s_branch .LBB0_915
.Lord_partial:
	v_readlane_b32 s5, v236, 21
	s_mov_b32 s48, s4
	s_mov_b32 s63, s2
	s_cmp_ge_u32 s2, 29
	s_cbranch_scc1 .LBB0_914
	s_branch .Lord_common
